# attention K / K-rope / V LDS-DMA: scalar running bases advanced by SALU + 32-bit per-lane offsets (3 64-bit VALU adds per tile per wave removed, both unit loops)
# baseline (speedup 1.0000x reference)
.LBB0_574:
	s_or_b64 exec, exec, s[10:11]
	v_lshl_add_u64 v[0:1], s[38:39], 0, v[122:123]
	s_lshl_b32 s10, s28, 6
	v_lshlrev_b64 v[0:1], 11, v[0:1]
	v_lshl_add_u64 v[0:1], s[8:9], 0, v[0:1]
	s_lshl_b32 s46, s10, 1
	s_mov_b32 s47, s39
	v_lshl_add_u64 v[0:1], v[0:1], 0, s[46:47]
	v_mov_b32_e32 v167, v121
	v_lshl_add_u64 v[180:181], v[0:1], 0, v[166:167]
	v_and_b32_e32 v237, 16, v191
	v_lshlrev_b32_e32 v237, 2, v237
	v_xor_b32_e32 v234, v237, v180
	v_mov_b32_e32 v235, v181
	global_load_dwordx4 v[112:115], v[234:235], off offset:1024
	s_waitcnt vmcnt(0)
	ds_write_b128 v119, v[104:107]
	s_and_saveexec_b64 s[10:11], s[4:5]
	ds_write_b128 v119, v[108:111] offset:8192
	s_or_b64 exec, exec, s[10:11]
	s_lshl_b32 s10, s53, 11
	s_and_b32 s11, s60, 7
	s_and_b32 s10, s10, 0x3800000
	s_lshl_b32 s11, s11, 7
	s_or_b32 s10, s10, s11
	s_mov_b32 s11, s39
	v_lshl_add_u64 v[170:171], v[160:161], 0, s[10:11]
	s_lshl_b32 s28, s53, 6
	v_lshl_add_u64 v[174:175], v[164:165], 0, s[10:11]
	s_add_u32 s92, s26, s10
	s_addc_u32 s93, s27, s11
	s_add_i32 s10, s62, 0x100
	s_and_b32 s28, s28, 0x1c0000
	s_mov_b32 s29, s39
	s_ashr_i32 s47, s10, 6
	v_lshl_add_u64 v[172:173], v[162:163], 0, s[28:29]
	s_add_u32 s94, s26, s28
	s_addc_u32 s95, s27, s29
	s_cmp_lt_i32 s47, 1
	ds_write_b128 v119, v[112:115] offset:24576
	s_waitcnt lgkmcnt(0)
	s_barrier
	s_cbranch_scc1 .LBB0_601
	v_mov_b32_e32 v14, v121
	v_mov_b32_e32 v15, v121
	v_mov_b32_e32 v0, v121
	v_mov_b32_e32 v1, v121
	v_mov_b32_e32 v2, v121
	v_mov_b32_e32 v3, v121
	v_mov_b32_e32 v4, v121
	v_mov_b32_e32 v5, v121
	v_mov_b32_e32 v6, v121
	v_mov_b32_e32 v7, v121
	v_mov_b32_e32 v8, v121
	v_mov_b32_e32 v9, v121
	v_mov_b32_e32 v10, v121
	v_mov_b32_e32 v11, v121
	v_mov_b32_e32 v12, v121
	v_mov_b32_e32 v13, v121
	v_mov_b32_e32 v141, 0
	v_mov_b64_e32 v[30:31], v[14:15]
	s_or_b32 s49, s63, 31
	s_sub_i32 s64, 0, s47
	s_mov_b32 s65, 1
	s_mov_b32 s66, 63
	s_mov_b64 s[96:97], s[92:93]
	s_mov_b64 s[100:101], s[94:95]
	v_subrev_u32_e32 v184, s92, v174
	v_subrev_u32_e32 v186, s94, v172
	v_xor_b32_e32 v188, v237, v170
	v_subrev_u32_e32 v188, s92, v188
	v_bfe_u32 v232, v191, 2, 2
	v_bfe_u32 v233, v191, 5, 1
	v_lshl_add_u32 v233, v233, 2, v232
	v_lshlrev_b32_e32 v238, 7, v233
	v_bfe_u32 v233, v191, 4, 1
	v_bfe_u32 v234, v191, 1, 1
	v_lshl_or_b32 v233, v233, 1, v234
	v_lshrrev_b32_e32 v232, 1, v232
	v_lshlrev_b32_e32 v232, 2, v232
	v_xor_b32_e32 v233, v233, v232
	v_lshl_add_u32 v238, v233, 4, v238
	v_and_b32_e32 v232, 1, v191
	v_lshl_add_u32 v238, v232, 3, v238
	v_xor_b32_e32 v239, 64, v238
	v_readfirstlane_b32 s99, v119
	v_mov_b64_e32 v[28:29], v[12:13]
	v_mov_b64_e32 v[26:27], v[10:11]
	v_mov_b64_e32 v[24:25], v[8:9]
	v_mov_b64_e32 v[22:23], v[6:7]
	v_mov_b64_e32 v[20:21], v[4:5]
	v_mov_b64_e32 v[18:19], v[2:3]
	v_mov_b64_e32 v[16:17], v[0:1]
	v_mov_b32_e32 v139, 0
	v_mov_b32_e32 v32, 0
	v_mov_b32_e32 v33, v141
	v_mov_b32_e32 v34, v141
	v_mov_b32_e32 v35, v141
	v_mov_b32_e32 v36, v141
	v_mov_b32_e32 v37, v141
	v_mov_b32_e32 v38, v141
	v_mov_b32_e32 v39, v141
	v_mov_b32_e32 v40, v141
	v_mov_b32_e32 v41, v141
	v_mov_b32_e32 v42, v141
	v_mov_b32_e32 v43, v141
	v_mov_b32_e32 v44, v141
	v_mov_b32_e32 v45, v141
	v_mov_b32_e32 v46, v141
	v_mov_b32_e32 v47, v141
	s_branch .LBB0_580

.LBB0_579:
	s_add_i32 s65, s65, 1
	s_add_i32 s66, s66, 64
	s_add_i32 s10, s64, s65
	s_add_u32 s96, s96, s40
	s_addc_u32 s97, s97, s41
	s_add_u32 s100, s100, s42
	s_addc_u32 s101, s101, s43
	s_cmp_eq_u32 s10, 1
	s_waitcnt lgkmcnt(0)
	s_barrier
	s_cbranch_scc1 .LBB0_602
.LBB0_580:
	s_cmp_lt_i32 s65, s47
	s_cselect_b64 s[50:51], -1, 0
	s_cmp_ge_i32 s65, s47
	s_cbranch_scc1 .LBB0_584
	s_and_b32 s10, s65, 1
	s_mul_i32 s11, s10, 0x3000
	s_add_i32 s11, s11, s99
	s_mov_b32 m0, s11
	s_nop 0
	global_load_lds_dwordx4 v184, s[96:97]
	s_cmp_lg_u64 s[4:5], 0
	s_cbranch_scc0 .LBB0_583
	s_add_i32 m0, s11, 0x2000
	s_nop 0
	global_load_lds_dwordx4 v186, s[100:101]
.LBB0_583:
	s_mulk_i32 s10, 0x2200
	s_add_i32 s10, s10, s99
	s_add_i32 m0, s10, 0x6000
	s_nop 0
	global_load_lds_dwordx4 v188, s[96:97]

.LBB0_606:
	s_or_b64 exec, exec, s[10:11]
	v_and_b32_e32 v237, 16, v191
	v_lshlrev_b32_e32 v237, 2, v237
	v_xor_b32_e32 v234, v237, v180
	v_mov_b32_e32 v235, v181
	global_load_dwordx4 v[112:115], v[234:235], off offset:1024
	s_waitcnt vmcnt(1)
	ds_write_b128 v119, v[104:107]
	s_and_saveexec_b64 s[10:11], s[4:5]
	ds_write_b128 v119, v[108:111] offset:8192
	s_or_b64 exec, exec, s[10:11]
	s_sub_i32 s10, 0x1000, s62
	s_ashr_i32 s50, s10, 6
	s_cmp_lt_i32 s50, 1
	s_waitcnt vmcnt(0)
	ds_write_b128 v119, v[112:115] offset:24576
	s_waitcnt lgkmcnt(0)
	s_barrier
	s_cbranch_scc1 .LBB0_633
	v_mov_b32_e32 v14, v121
	v_mov_b32_e32 v15, v121
	v_mov_b32_e32 v0, v121
	v_mov_b32_e32 v1, v121
	v_mov_b32_e32 v2, v121
	v_mov_b32_e32 v3, v121
	v_mov_b32_e32 v4, v121
	v_mov_b32_e32 v5, v121
	v_mov_b32_e32 v6, v121
	v_mov_b32_e32 v7, v121
	v_mov_b32_e32 v8, v121
	v_mov_b32_e32 v9, v121
	v_mov_b32_e32 v10, v121
	v_mov_b32_e32 v11, v121
	v_mov_b32_e32 v12, v121
	v_mov_b32_e32 v13, v121
	v_mov_b32_e32 v143, 0
	v_mov_b64_e32 v[30:31], v[14:15]
	s_or_b32 s51, s47, 31
	s_sub_i32 s62, 0, s50
	s_mov_b32 s63, 1
	s_mov_b32 s64, 63
	v_mov_b64_e32 v[28:29], v[12:13]
	v_mov_b64_e32 v[26:27], v[10:11]
	v_mov_b64_e32 v[24:25], v[8:9]
	v_mov_b64_e32 v[22:23], v[6:7]
	v_mov_b64_e32 v[20:21], v[4:5]
	v_mov_b64_e32 v[18:19], v[2:3]
	v_mov_b64_e32 v[16:17], v[0:1]
	v_mov_b32_e32 v141, 0
	v_mov_b32_e32 v32, 0
	v_mov_b32_e32 v33, v143
	v_mov_b32_e32 v34, v143
	v_mov_b32_e32 v35, v143
	v_mov_b32_e32 v36, v143
	v_mov_b32_e32 v37, v143
	v_mov_b32_e32 v38, v143
	v_mov_b32_e32 v39, v143
	v_mov_b32_e32 v40, v143
	v_mov_b32_e32 v41, v143
	v_mov_b32_e32 v42, v143
	v_mov_b32_e32 v43, v143
	v_mov_b32_e32 v44, v143
	v_mov_b32_e32 v45, v143
	v_mov_b32_e32 v46, v143
	v_mov_b32_e32 v47, v143
	v_bfe_u32 v232, v191, 2, 2
	v_bfe_u32 v233, v191, 5, 1
	v_lshl_add_u32 v233, v233, 2, v232
	v_lshlrev_b32_e32 v238, 7, v233
	v_bfe_u32 v233, v191, 4, 1
	v_bfe_u32 v234, v191, 1, 1
	v_lshl_or_b32 v233, v233, 1, v234
	v_lshrrev_b32_e32 v232, 1, v232
	v_lshlrev_b32_e32 v232, 2, v232
	v_xor_b32_e32 v233, v233, v232
	v_lshl_add_u32 v238, v233, 4, v238
	v_and_b32_e32 v232, 1, v191
	v_lshl_add_u32 v238, v232, 3, v238
	v_xor_b32_e32 v239, 64, v238
	v_readfirstlane_b32 s99, v119
	v_xor_b32_e32 v170, v237, v170
	v_subrev_u32_e32 v174, s92, v174
	v_subrev_u32_e32 v172, s94, v172
	v_subrev_u32_e32 v170, s92, v170
	s_branch .LBB0_612

.LBB0_611:
	s_add_i32 s63, s63, 1
	s_add_i32 s64, s64, 64
	s_add_i32 s10, s62, s63
	s_add_u32 s92, s92, s40
	s_addc_u32 s93, s93, s41
	s_add_u32 s94, s94, s42
	s_addc_u32 s95, s95, s43
	s_cmp_eq_u32 s10, 1
	s_waitcnt lgkmcnt(0)
	s_barrier
	s_cbranch_scc1 .LBB0_634
.LBB0_612:
	s_cmp_lt_i32 s63, s50
	s_cselect_b64 s[48:49], -1, 0
	s_cmp_ge_i32 s63, s50
	s_cbranch_scc1 .LBB0_616
	s_and_b32 s10, s63, 1
	s_mul_i32 s11, s10, 0x3000
	s_add_i32 s11, s11, s99
	s_mov_b32 m0, s11
	s_nop 0
	global_load_lds_dwordx4 v174, s[92:93]
	s_cmp_lg_u64 s[4:5], 0
	s_cbranch_scc0 .LBB0_615
	s_add_i32 m0, s11, 0x2000
	s_nop 0
	global_load_lds_dwordx4 v172, s[94:95]
.LBB0_615:
	s_mulk_i32 s10, 0x2200
	s_add_i32 s10, s10, s99
	s_add_i32 m0, s10, 0x6000
	s_nop 0
	global_load_lds_dwordx4 v170, s[92:93]
